# weight conversion split: w_up+w_out+1024 w_down items before the in-proj units, remaining w_down items after them (3-unit workgroups), no conversion work left in P2
# speedup vs baseline: 1.0030x; 1.0030x over previous
; #define LAS __attribute__((address_space(3)))
; __device__ __forceinline__ void transpose_tile(const float* __restrict__ W, int K, int N, bf16* __restrict__ WT, const float* __restrict__ ga, const float* __restrict__ gb, int gsplit, LAS float* scr, int item, int lane) {
;     const int nkb = K / 64, nb = item / nkb, kb = item % nkb, k0 = 64 * kb, n0 = 64 * nb;
;     const int c = lane & 15, kq = lane >> 4;
; __global__ void __launch_bounds__(NT, 2) fwd_mega(Args A) {
;     ...
;         const int rem = NU % G, NH = (rem == 0) ? G : G - rem, hi = (rem == 0) ? cid : cid - rem;
;         if (hi >= 0) {
;             constexpr int I_UP = (D / 64) * (FF / 64);
;             LAS float* scr = (LAS float*)(lds + wave * 16640);
;             for (int it = hi * NW + wave; it < I_UP; it += NH * NW) transpose_tile(A.w_up, D, FF, WupT, A.g_ffn, A.g_ffn, D, scr, it, lane);
.LBB0_464:
	s_add_u32 s8, s28, 0x1900000
	s_addc_u32 s9, s29, 0
	s_abs_i32 s0, s30
	v_cvt_f32_u32_e32 v0, s0
	s_sub_i32 s1, 0, s0
	v_rcp_iflag_f32_e32 v0, v0
	s_nop 0
	v_mul_f32_e32 v0, 0x4f7ffffe, v0
	v_cvt_u32_f32_e32 v0, v0
	s_nop 0
	v_readfirstlane_b32 s2, v0
	s_mul_i32 s1, s1, s2
	s_mul_hi_u32 s1, s2, s1
	s_add_i32 s2, s2, s1
	s_mul_hi_u32 s1, s2, 0x380
	s_mul_i32 s1, s1, s0
	s_sub_i32 s1, 0x380, s1
	s_sub_i32 s2, s1, s0
	s_cmp_ge_u32 s1, s0
	s_cselect_b32 s1, s2, s1
	s_sub_i32 s2, s1, s0
	s_cmp_ge_u32 s1, s0
	s_cselect_b32 s1, s2, s1
	s_sub_i32 s0, s12, s1
	s_cmp_lt_i32 s0, 0
	s_cbranch_scc1 .LBB0_501
	s_lshl_b32 s0, s0, 3
	v_readlane_b32 s2, v255, 3
	s_sub_i32 s4, s30, s1
	s_nop 1
	s_add_i32 s60, s0, s2
	s_lshl_b32 s61, s4, 3
	s_movk_i32 s62, 0xc00
	s_cmp_ge_u32 s60, s62
	s_cbranch_scc1 .Lcvd_end
	v_readlane_b32 s63, v255, 3
	v_and_b32_e32 v122, 63, v160
	v_and_b32_e32 v112, 15, v122
	v_lshlrev_b32_e32 v112, 4, v112
	v_lshrrev_b32_e32 v113, 4, v122
	v_lshlrev_b32_e32 v114, 2, v113
	v_and_b32_e32 v115, 7, v122
	v_lshrrev_b32_e32 v116, 3, v122
	s_mulk_i32 s63, 0x4100
	s_movk_i32 s80, 0x104
	v_mad_u32_u24 v117, v113, s80, v112
	v_add_u32_e32 v117, s63, v117
	s_movk_i32 s80, 0x820
	v_lshlrev_b32_e32 v119, 2, v116
	v_mad_u32_u24 v118, v115, s80, v119
	v_add_u32_e32 v118, s63, v118
	v_add_u32_e32 v119, 0x400, v118
	v_lshlrev_b32_e32 v115, 4, v115
	s_mov_b32 s75, s60
	s_branch .Lcvd_p0_m0

; __global__ void __launch_bounds__(NT, 2) fwd_mega(Args A) {
;     ...
;     if (!(vcu2 & 1)) convert_out_down(A, lds, vcu2, G);
; #pragma unroll 1
;     for (int u = vcu2; u < 1536; u += G) {
;         if (u < 512) attn_unit(PROJ, ws, lds, u);
.LBB0_553:
	s_or_b64 exec, exec, s[2:3]
	s_add_u32 s6, s28, 0x1100000
	s_addc_u32 s7, s29, 0
	s_bitcmp1_b32 s96, 0
	s_cselect_b64 s[22:23], -1, 0
	s_and_b64 vcc, exec, s[22:23]
	s_waitcnt lgkmcnt(0)
	s_barrier
	s_cbranch_vccnz .LBB0_594
.LBB0_594:
	s_add_u32 s10, s28, 0x9900000
	s_addc_u32 s11, s29, 0
	s_add_u32 s20, s28, 0x40000
	s_addc_u32 s21, s29, 0
	s_cmpk_gt_i32 s96, 0x5ff
	s_cbranch_scc1 .LBB0_621
	s_add_u32 s42, s28, 0x1c0000
	s_addc_u32 s43, s29, 0
	s_add_u32 s47, s28, 0x200800
	s_addc_u32 s53, s29, 0
	v_mbcnt_hi_u32_b32 v167, -1, v161
	s_add_u32 s58, s28, 0x201800
	v_and_b32_e32 v0, 64, v167
	s_addc_u32 s59, s29, 0
	s_mov_b32 s45, 0
	v_mov_b32_e32 v163, 0
	s_movk_i32 s60, 0x1c00
	s_mov_b32 s46, 0x3a800000
	s_mov_b32 s61, 0xf800000
	v_mov_b32_e32 v166, 0x260
	s_movk_i32 s62, 0x120
	s_mov_b64 s[48:49], 0x9900800
	s_mov_b32 s63, 0x9900000
	s_movk_i32 s64, 0x110
	s_add_i32 s65, 0, 0x11000
	s_add_i32 s66, 0, 0x19800
	s_mov_b32 s67, 0xf149f2ca
	v_xor_b32_e32 v168, 16, v167
	v_add_u32_e32 v169, 64, v0
	v_xor_b32_e32 v170, 32, v167
	v_mov_b32_e32 v171, 0xf149f2ca
	s_mov_b32 s68, s96
	s_branch .LBB0_598

; __device__ __forceinline__ void xcd_barrier(const XcdBarrier& b) {
;     asm volatile("s_waitcnt vmcnt(0)" ::: "memory");
;     __syncthreads();
;     if (threadIdx.x == 0) {
;         unsigned* bar = b.bar;
;         __builtin_amdgcn_s_waitcnt(0);
;         unsigned nloc = b.st[0], nx = b.st[1];
;         if (nloc == 0u) { xcd_barrier_complete(bar, b.x, nloc, nx); b.st[0] = nloc; b.st[1] = nx; }
; __global__ void __launch_bounds__(NT, 2) fwd_mega(Args A) {
;     ...
;     if (vcu2 & 1) convert_out_down(A, lds, vcu2, G);
;     xcd_barrier(xbar);
.LBB0_621:
	s_and_b64 vcc, exec, s[22:23]
	s_cbranch_vccz .LBB0_662
.LBB0_662:
	s_waitcnt vmcnt(0)
	s_waitcnt lgkmcnt(0)
	s_barrier
	s_and_saveexec_b64 s[2:3], s[88:89]
	s_cbranch_execz .LBB0_714
	s_add_i32 s0, 0, 0x23fc0
	v_mov_b32_e32 v0, s0
	s_waitcnt vmcnt(0) expcnt(0) lgkmcnt(0)
	ds_read_b32 v2, v0
	s_add_i32 s0, 0, 0x23fc4
	v_mov_b32_e32 v0, s0
	ds_read_b32 v0, v0
	s_waitcnt lgkmcnt(1)
	v_cmp_ne_u32_e32 vcc, 0, v2
	s_cbranch_vccnz .LBB0_678
	s_add_u32 s4, s28, 0x210200
	s_addc_u32 s5, s29, 0
	s_add_u32 s14, s28, 0x210400
	s_addc_u32 s15, s29, 0
	s_add_u32 s16, s28, 0x210500
	s_addc_u32 s17, s29, 0
	s_add_u32 s18, s28, 0x210600
	s_addc_u32 s19, s29, 0
	s_add_u32 s22, s28, 0x210700
	s_addc_u32 s23, s29, 0
	s_add_u32 s24, s28, 0x210800
	s_addc_u32 s25, s29, 0
	s_add_u32 s40, s28, 0x210900
	s_addc_u32 s41, s29, 0
	s_add_u32 s42, s28, 0x210a00
	s_addc_u32 s43, s29, 0
	s_add_u32 s44, s28, 0x210b00
	s_addc_u32 s45, s29, 0
	s_add_u32 s46, s28, 0x210c00
	s_addc_u32 s47, s29, 0
	s_add_u32 s48, s28, 0x210d00
	s_addc_u32 s49, s29, 0
	s_add_u32 s50, s28, 0x210e00
	s_addc_u32 s51, s29, 0
	s_add_u32 s52, s28, 0x210f00
	s_addc_u32 s53, s29, 0
	s_add_u32 s54, s28, 0x211000
	s_addc_u32 s55, s29, 0
	s_add_u32 s56, s28, 0x211100
	s_addc_u32 s57, s29, 0
	s_add_u32 s58, s28, 0x211200
	v_readlane_b32 s0, v255, 0
	s_addc_u32 s59, s29, 0
	s_mul_i32 s0, s31, s0
	s_add_u32 s60, s28, 0x211300
	s_mul_i32 s0, s0, s30
	s_addc_u32 s61, s29, 0
	s_mov_b32 s1, 1
	v_mov_b32_e32 v16, 0
	s_branch .LBB0_666
